# F1 GEMM K-loop: A-fragment LDS reads of phases 2/4 issued inside the preceding MFMA segment (second fragment register set); saddr-form LDS-DMA
# speedup vs baseline: 1.0078x; 1.0078x over previous
; #define PG8_STAGE(bufoff, gbase, voff) do { _Pragma("unroll") for (int _i = 0; _i < 2; ++_i) \
;         __builtin_amdgcn_global_load_lds((const unsigned*)((const char*)(gbase) + (voff)[_i]), (PG8_LAS unsigned*)(lds + (bufoff) + ldsw + _i * 8192), 16, 0, 0); } while (0)
; #define PG8_LDA(dst, b, h) do { _Pragma("unroll") for (int m = 0; m < 4; ++m) _Pragma("unroll") for (int k = 0; k < 2; ++k) dst[m][k] = *(const PG8_LAS bf16x8*)(lds + PG8_SA(b, h) + aoff + m * 2048 + k * 1024); } while (0)
; #define PG8_LDB(dst, b, h) do { _Pragma("unroll") for (int n = 0; n < 2; ++n) _Pragma("unroll") for (int k = 0; k < 2; ++k) dst[n][k] = *(const PG8_LAS bf16x8*)(lds + PG8_SB(b, h) + boff + n * 2048 + k * 1024); } while (0)
; #define PG8_MMA(ai, bj, At, Bt) do { __builtin_amdgcn_s_setprio(1); _Pragma("unroll") for (int m = 0; m < 4; ++m) _Pragma("unroll") for (int n = 0; n < 2; ++n) _Pragma("unroll") for (int k = 0; k < 2; ++k) \
;         acc[ai][bj][m][n] = __builtin_amdgcn_mfma_f32_16x16x32_bf16(Bt[n][k], At[m][k], acc[ai][bj][m][n], 0, 0, 0); __builtin_amdgcn_s_setprio(0); } while (0)
; #define PG8_WAIT_V(n) asm volatile("s_waitcnt vmcnt(" #n ")" ::: "memory")
; #define PG8_WAIT_L(n) asm volatile("s_waitcnt lgkmcnt(" #n ")" ::: "memory")
; template <class Epi, class Sched, bool ALIGN_EPI = true, bool SP2 = true>
; __device__ __forceinline__ void gemm_phase(PG8_LAS unsigned char* lds, const Gemm g, const Sched& S, const Epi& E, const int tid) {
;     ...
;             const bool last = (t == nt - 2);
;             const char* a1 = cA + (size_t)(t + 1) * kstep;
;             const char* a2 = last ? nA : cA + (size_t)(t + 2) * kstep; const char* b2 = last ? nB : cB + (size_t)(t + 2) * kstep;
;             const char* a3 = a2 + kstep; const char* b3 = b2 + kstep;
;             if (last && has_next) S.a_ready(nxt);
;             if constexpr (SP2) {
;             PG8_LDB(B0, 0, 0); PG8_LDB(B1, 0, 1); PG8_SCHED; PG8_LDA(At, 0, 0); PG8_STAGE(PG8_SA(1, 1), a1 + hstepA, voffA);
;             PG8_WAIT_V(8); PG8_WAIT_L(0); PG8_BAR; PG8_MMA(0, 0, At, B0); PG8_MMA(0, 1, At, B1); PG8_BAR; PG8_SCHED;
;             PG8_LDA(At, 0, 1); PG8_STAGE(PG8_SB(0, 0), b2, voffB); PG8_STAGE(PG8_SB(0, 1), b2 + hstepB, voffB); PG8_STAGE(PG8_SA(0, 0), a2, voffA);
;             PG8_WAIT_V(8); PG8_WAIT_L(0); PG8_BAR; PG8_MMA(1, 0, At, B0); PG8_MMA(1, 1, At, B1); PG8_BAR; PG8_SCHED;
.LBB0_1319:
	s_add_u32 s28, s62, 0xfff80080
	s_addc_u32 s29, s63, -1
	s_add_i32 s30, 0, 0x10000
	s_cmp_eq_u32 s52, 28
	s_cselect_b32 s67, s24, s29
	s_cselect_b32 s66, s25, s28
	v_add_u32_e32 v145, s30, v142
	s_cselect_b32 s65, s26, s51
	s_cselect_b32 s64, s27, s49
	s_add_i32 s31, 0, 0x14000
	ds_read_b128 v[146:149], v145
	ds_read_b128 v[150:153], v145 offset:1024
	ds_read_b128 v[154:157], v145 offset:2048
	ds_read_b128 v[158:161], v145 offset:3072
	v_add_u32_e32 v145, s31, v142
	ds_read_b128 v[162:165], v145
	ds_read_b128 v[166:169], v145 offset:1024
	ds_read_b128 v[170:173], v145 offset:2048
	ds_read_b128 v[174:177], v145 offset:3072
	s_add_i32 m0, s22, 0xc000
	ds_read_b128 v[178:181], v144
	ds_read_b128 v[182:185], v144 offset:1024
	ds_read_b128 v[186:189], v144 offset:2048
	ds_read_b128 v[190:193], v144 offset:3072
	ds_read_b128 v[194:197], v144 offset:4096
	ds_read_b128 v[200:203], v144 offset:5120
	ds_read_b128 v[206:209], v144 offset:6144
	ds_read_b128 v[210:213], v144 offset:7168
	global_load_lds_dwordx4 v138, s[62:63]
	s_add_i32 m0, s22, 0xe000
	s_nop 0
	global_load_lds_dwordx4 v140, s[62:63]
	s_waitcnt vmcnt(8)
	s_waitcnt lgkmcnt(0)
	s_barrier
	s_setprio 1
	s_waitcnt lgkmcnt(0)
	v_mfma_f32_16x16x32_bf16 v[126:129], v[146:149], v[178:181], v[126:129]
	v_mfma_f32_16x16x32_bf16 v[118:121], v[154:157], v[178:181], v[118:121]
	ds_read_b128 v[218:221], v144 offset:16384
	v_mfma_f32_16x16x32_bf16 v[110:113], v[146:149], v[186:189], v[110:113]
	v_mfma_f32_16x16x32_bf16 v[102:105], v[154:157], v[186:189], v[102:105]
	v_mfma_f32_16x16x32_bf16 v[92:95], v[146:149], v[194:197], v[92:95]
	v_mfma_f32_16x16x32_bf16 v[84:87], v[154:157], v[194:197], v[84:87]
	ds_read_b128 v[222:225], v144 offset:17408
	v_mfma_f32_16x16x32_bf16 v[76:79], v[146:149], v[206:209], v[76:79]
	v_mfma_f32_16x16x32_bf16 v[68:71], v[154:157], v[206:209], v[68:71]
	v_mfma_f32_16x16x32_bf16 v[126:129], v[150:153], v[182:185], v[126:129]
	v_mfma_f32_16x16x32_bf16 v[118:121], v[158:161], v[182:185], v[118:121]
	ds_read_b128 v[226:229], v144 offset:18432
	v_mfma_f32_16x16x32_bf16 v[110:113], v[150:153], v[190:193], v[110:113]
	v_mfma_f32_16x16x32_bf16 v[102:105], v[158:161], v[190:193], v[102:105]
	v_mfma_f32_16x16x32_bf16 v[92:95], v[150:153], v[200:203], v[92:95]
	v_mfma_f32_16x16x32_bf16 v[84:87], v[158:161], v[200:203], v[84:87]
	ds_read_b128 v[230:233], v144 offset:19456
	v_mfma_f32_16x16x32_bf16 v[76:79], v[150:153], v[210:213], v[76:79]
	v_mfma_f32_16x16x32_bf16 v[68:71], v[158:161], v[210:213], v[68:71]
	s_setprio 0
	s_setprio 1
	v_mfma_f32_16x16x32_bf16 v[122:125], v[162:165], v[178:181], v[122:125]
	v_mfma_f32_16x16x32_bf16 v[114:117], v[170:173], v[178:181], v[114:117]
	ds_read_b128 v[234:237], v144 offset:20480
	v_mfma_f32_16x16x32_bf16 v[106:109], v[162:165], v[186:189], v[106:109]
	v_mfma_f32_16x16x32_bf16 v[98:101], v[170:173], v[186:189], v[98:101]
	v_mfma_f32_16x16x32_bf16 v[88:91], v[162:165], v[194:197], v[88:91]
	v_mfma_f32_16x16x32_bf16 v[80:83], v[170:173], v[194:197], v[80:83]
	ds_read_b128 v[238:241], v144 offset:21504
	v_mfma_f32_16x16x32_bf16 v[72:75], v[162:165], v[206:209], v[72:75]
	v_mfma_f32_16x16x32_bf16 v[64:67], v[170:173], v[206:209], v[64:67]
	v_mfma_f32_16x16x32_bf16 v[122:125], v[166:169], v[182:185], v[122:125]
	v_mfma_f32_16x16x32_bf16 v[114:117], v[174:177], v[182:185], v[114:117]
	ds_read_b128 v[242:245], v144 offset:22528
	v_mfma_f32_16x16x32_bf16 v[106:109], v[166:169], v[190:193], v[106:109]
	v_mfma_f32_16x16x32_bf16 v[98:101], v[174:177], v[190:193], v[98:101]
	v_mfma_f32_16x16x32_bf16 v[88:91], v[166:169], v[200:203], v[88:91]
	v_mfma_f32_16x16x32_bf16 v[80:83], v[174:177], v[200:203], v[80:83]
	ds_read_b128 v[246:249], v144 offset:23552
	v_mfma_f32_16x16x32_bf16 v[72:75], v[166:169], v[210:213], v[72:75]
	v_mfma_f32_16x16x32_bf16 v[64:67], v[174:177], v[210:213], v[64:67]
	s_setprio 0
	s_barrier
	s_add_i32 s28, s30, s21
	s_mov_b32 m0, s28
	s_nop 0
	global_load_lds_dwordx4 v134, s[64:65]
	s_add_i32 m0, s28, 0x2000
	s_add_u32 s28, s64, 0x80000
	s_addc_u32 s29, s65, 0
	s_add_i32 s30, s31, s21
	global_load_lds_dwordx4 v130, s[64:65]
	s_mov_b32 m0, s30
	s_nop 0
	global_load_lds_dwordx4 v134, s[28:29]
	s_add_i32 m0, s30, 0x2000
	s_nop 0
	global_load_lds_dwordx4 v130, s[28:29]
	s_mov_b32 m0, s22
	s_nop 0
	global_load_lds_dwordx4 v136, s[66:67]
	s_mov_b32 m0, s23
	s_nop 0
	global_load_lds_dwordx4 v132, s[66:67]
	s_waitcnt vmcnt(6)
	s_waitcnt lgkmcnt(0)
	s_barrier
	s_setprio 1
	s_waitcnt lgkmcnt(0)
	v_mfma_f32_16x16x32_bf16 v[60:63], v[146:149], v[218:221], v[60:63]
	v_mfma_f32_16x16x32_bf16 v[52:55], v[154:157], v[218:221], v[52:55]
	v_mfma_f32_16x16x32_bf16 v[44:47], v[146:149], v[226:229], v[44:47]
	v_mfma_f32_16x16x32_bf16 v[36:39], v[154:157], v[226:229], v[36:39]
	v_mfma_f32_16x16x32_bf16 v[28:31], v[146:149], v[234:237], v[28:31]
	v_mfma_f32_16x16x32_bf16 v[20:23], v[154:157], v[234:237], v[20:23]
	v_mfma_f32_16x16x32_bf16 v[12:15], v[146:149], v[242:245], v[12:15]
	v_mfma_f32_16x16x32_bf16 v[4:7], v[154:157], v[242:245], v[4:7]
	v_mfma_f32_16x16x32_bf16 v[60:63], v[150:153], v[222:225], v[60:63]
	v_mfma_f32_16x16x32_bf16 v[52:55], v[158:161], v[222:225], v[52:55]
	v_mfma_f32_16x16x32_bf16 v[44:47], v[150:153], v[230:233], v[44:47]
	v_mfma_f32_16x16x32_bf16 v[36:39], v[158:161], v[230:233], v[36:39]
	v_mfma_f32_16x16x32_bf16 v[28:31], v[150:153], v[238:241], v[28:31]
	v_mfma_f32_16x16x32_bf16 v[20:23], v[158:161], v[238:241], v[20:23]
	v_mfma_f32_16x16x32_bf16 v[12:15], v[150:153], v[246:249], v[12:15]
	v_mfma_f32_16x16x32_bf16 v[4:7], v[158:161], v[246:249], v[4:7]
	s_setprio 0
	s_setprio 1
	v_mfma_f32_16x16x32_bf16 v[56:59], v[162:165], v[218:221], v[56:59]
	v_mfma_f32_16x16x32_bf16 v[48:51], v[170:173], v[218:221], v[48:51]
	v_mfma_f32_16x16x32_bf16 v[40:43], v[162:165], v[226:229], v[40:43]
	v_mfma_f32_16x16x32_bf16 v[32:35], v[170:173], v[226:229], v[32:35]
	v_mfma_f32_16x16x32_bf16 v[24:27], v[162:165], v[234:237], v[24:27]
	v_mfma_f32_16x16x32_bf16 v[16:19], v[170:173], v[234:237], v[16:19]
	v_mfma_f32_16x16x32_bf16 v[8:11], v[162:165], v[242:245], v[8:11]
	v_mfma_f32_16x16x32_bf16 v[0:3], v[170:173], v[242:245], v[0:3]
	v_mfma_f32_16x16x32_bf16 v[56:59], v[166:169], v[222:225], v[56:59]
	v_mfma_f32_16x16x32_bf16 v[48:51], v[174:177], v[222:225], v[48:51]
	v_mfma_f32_16x16x32_bf16 v[40:43], v[166:169], v[230:233], v[40:43]
	v_mfma_f32_16x16x32_bf16 v[32:35], v[174:177], v[230:233], v[32:35]
	v_mfma_f32_16x16x32_bf16 v[24:27], v[166:169], v[238:241], v[24:27]
	v_mfma_f32_16x16x32_bf16 v[16:19], v[174:177], v[238:241], v[16:19]
	v_mfma_f32_16x16x32_bf16 v[8:11], v[166:169], v[246:249], v[8:11]
	v_mfma_f32_16x16x32_bf16 v[0:3], v[174:177], v[246:249], v[0:3]
	s_setprio 0
	s_barrier
; #define PG8_STAGE(bufoff, gbase, voff) do { _Pragma("unroll") for (int _i = 0; _i < 2; ++_i) \
;         __builtin_amdgcn_global_load_lds((const unsigned*)((const char*)(gbase) + (voff)[_i]), (PG8_LAS unsigned*)(lds + (bufoff) + ldsw + _i * 8192), 16, 0, 0); } while (0)
; #define PG8_LDA(dst, b, h) do { _Pragma("unroll") for (int m = 0; m < 4; ++m) _Pragma("unroll") for (int k = 0; k < 2; ++k) dst[m][k] = *(const PG8_LAS bf16x8*)(lds + PG8_SA(b, h) + aoff + m * 2048 + k * 1024); } while (0)
; #define PG8_LDB(dst, b, h) do { _Pragma("unroll") for (int n = 0; n < 2; ++n) _Pragma("unroll") for (int k = 0; k < 2; ++k) dst[n][k] = *(const PG8_LAS bf16x8*)(lds + PG8_SB(b, h) + boff + n * 2048 + k * 1024); } while (0)
; #define PG8_MMA(ai, bj, At, Bt) do { __builtin_amdgcn_s_setprio(1); _Pragma("unroll") for (int m = 0; m < 4; ++m) _Pragma("unroll") for (int n = 0; n < 2; ++n) _Pragma("unroll") for (int k = 0; k < 2; ++k) \
;         acc[ai][bj][m][n] = __builtin_amdgcn_mfma_f32_16x16x32_bf16(Bt[n][k], At[m][k], acc[ai][bj][m][n], 0, 0, 0); __builtin_amdgcn_s_setprio(0); } while (0)
; #define PG8_WAIT_V(n) asm volatile("s_waitcnt vmcnt(" #n ")" ::: "memory")
; #define PG8_WAIT_L(n) asm volatile("s_waitcnt lgkmcnt(" #n ")" ::: "memory")
; #define PG8_BAR __builtin_amdgcn_s_barrier()
; #define PG8_SCHED __builtin_amdgcn_sched_barrier(0)
; template <class Epi, class Sched, bool ALIGN_EPI = true, bool SP2 = true>
; __device__ __forceinline__ void gemm_phase(PG8_LAS unsigned char* lds, const Gemm g, const Sched& S, const Epi& E, const int tid) {
;     ...
;             PG8_LDB(B0, 1, 0); PG8_LDB(B1, 1, 1); PG8_SCHED; PG8_LDA(At, 1, 0); PG8_STAGE(PG8_SA(0, 1), a2 + hstepA, voffA);
;             PG8_WAIT_V(8); PG8_WAIT_L(0); PG8_BAR; PG8_MMA(0, 0, At, B0); PG8_MMA(0, 1, At, B1); PG8_BAR; PG8_SCHED;
;             PG8_LDA(At, 1, 1); PG8_STAGE(PG8_SB(1, 0), b3, voffB); PG8_STAGE(PG8_SB(1, 1), b3 + hstepB, voffB); PG8_STAGE(PG8_SA(1, 0), a3, voffA);
;             PG8_WAIT_V(8); PG8_WAIT_L(0); PG8_BAR; PG8_MMA(1, 0, At, B0); PG8_MMA(1, 1, At, B1); PG8_BAR; PG8_SCHED;
	s_add_i32 s30, 0, 0x18000
	v_add_u32_e32 v145, s30, v142
	s_add_i32 s31, 0, 0x1c000
	ds_read_b128 v[146:149], v145
	ds_read_b128 v[150:153], v145 offset:1024
	ds_read_b128 v[154:157], v145 offset:2048
	ds_read_b128 v[158:161], v145 offset:3072
	v_add_u32_e32 v145, s31, v142
	ds_read_b128 v[162:165], v145
	ds_read_b128 v[166:169], v145 offset:1024
	ds_read_b128 v[170:173], v145 offset:2048
	ds_read_b128 v[174:177], v145 offset:3072
	s_add_u32 s28, s66, 0x80000
	s_addc_u32 s29, s67, 0
	s_mov_b32 m0, s61
	ds_read_b128 v[178:181], v144 offset:32768
	ds_read_b128 v[182:185], v144 offset:33792
	ds_read_b128 v[186:189], v144 offset:34816
	ds_read_b128 v[190:193], v144 offset:35840
	ds_read_b128 v[194:197], v144 offset:36864
	ds_read_b128 v[200:203], v144 offset:37888
	ds_read_b128 v[206:209], v144 offset:38912
	ds_read_b128 v[210:213], v144 offset:39936
	global_load_lds_dwordx4 v136, s[28:29]
	s_mov_b32 m0, s70
	s_nop 0
	global_load_lds_dwordx4 v132, s[28:29]
	s_waitcnt vmcnt(8)
	s_waitcnt lgkmcnt(0)
	s_barrier
	s_setprio 1
	s_waitcnt lgkmcnt(0)
	v_mfma_f32_16x16x32_bf16 v[126:129], v[146:149], v[178:181], v[126:129]
	v_mfma_f32_16x16x32_bf16 v[118:121], v[154:157], v[178:181], v[118:121]
	ds_read_b128 v[218:221], v144 offset:49152
	v_mfma_f32_16x16x32_bf16 v[110:113], v[146:149], v[186:189], v[110:113]
	v_mfma_f32_16x16x32_bf16 v[102:105], v[154:157], v[186:189], v[102:105]
	v_mfma_f32_16x16x32_bf16 v[92:95], v[146:149], v[194:197], v[92:95]
	v_mfma_f32_16x16x32_bf16 v[84:87], v[154:157], v[194:197], v[84:87]
	ds_read_b128 v[222:225], v144 offset:50176
	v_mfma_f32_16x16x32_bf16 v[76:79], v[146:149], v[206:209], v[76:79]
	v_mfma_f32_16x16x32_bf16 v[68:71], v[154:157], v[206:209], v[68:71]
	v_mfma_f32_16x16x32_bf16 v[126:129], v[150:153], v[182:185], v[126:129]
	v_mfma_f32_16x16x32_bf16 v[118:121], v[158:161], v[182:185], v[118:121]
	ds_read_b128 v[226:229], v144 offset:51200
	v_mfma_f32_16x16x32_bf16 v[110:113], v[150:153], v[190:193], v[110:113]
	v_mfma_f32_16x16x32_bf16 v[102:105], v[158:161], v[190:193], v[102:105]
	v_mfma_f32_16x16x32_bf16 v[92:95], v[150:153], v[200:203], v[92:95]
	v_mfma_f32_16x16x32_bf16 v[84:87], v[158:161], v[200:203], v[84:87]
	ds_read_b128 v[230:233], v144 offset:52224
	v_mfma_f32_16x16x32_bf16 v[76:79], v[150:153], v[210:213], v[76:79]
	v_mfma_f32_16x16x32_bf16 v[68:71], v[158:161], v[210:213], v[68:71]
	s_setprio 0
	s_setprio 1
	v_mfma_f32_16x16x32_bf16 v[122:125], v[162:165], v[178:181], v[122:125]
	v_mfma_f32_16x16x32_bf16 v[114:117], v[170:173], v[178:181], v[114:117]
	ds_read_b128 v[234:237], v144 offset:53248
	v_mfma_f32_16x16x32_bf16 v[106:109], v[162:165], v[186:189], v[106:109]
	v_mfma_f32_16x16x32_bf16 v[98:101], v[170:173], v[186:189], v[98:101]
	v_mfma_f32_16x16x32_bf16 v[88:91], v[162:165], v[194:197], v[88:91]
	v_mfma_f32_16x16x32_bf16 v[80:83], v[170:173], v[194:197], v[80:83]
	ds_read_b128 v[238:241], v144 offset:54272
	v_mfma_f32_16x16x32_bf16 v[72:75], v[162:165], v[206:209], v[72:75]
	v_mfma_f32_16x16x32_bf16 v[64:67], v[170:173], v[206:209], v[64:67]
	v_mfma_f32_16x16x32_bf16 v[122:125], v[166:169], v[182:185], v[122:125]
	v_mfma_f32_16x16x32_bf16 v[114:117], v[174:177], v[182:185], v[114:117]
	ds_read_b128 v[242:245], v144 offset:55296
	v_mfma_f32_16x16x32_bf16 v[106:109], v[166:169], v[190:193], v[106:109]
	v_mfma_f32_16x16x32_bf16 v[98:101], v[174:177], v[190:193], v[98:101]
	v_mfma_f32_16x16x32_bf16 v[88:91], v[166:169], v[200:203], v[88:91]
	v_mfma_f32_16x16x32_bf16 v[80:83], v[174:177], v[200:203], v[80:83]
	ds_read_b128 v[246:249], v144 offset:56320
	v_mfma_f32_16x16x32_bf16 v[72:75], v[166:169], v[210:213], v[72:75]
	v_mfma_f32_16x16x32_bf16 v[64:67], v[174:177], v[210:213], v[64:67]
	s_setprio 0
	s_barrier
	s_add_i32 s28, s30, s21
	s_add_u32 s4, s64, 0x80
	s_addc_u32 s5, s65, 0
	s_mov_b32 m0, s28
	s_nop 0
	global_load_lds_dwordx4 v134, s[4:5]
	s_add_i32 m0, s28, 0x2000
	s_add_u32 s28, s64, 0x80080
	s_addc_u32 s29, s65, 0
	s_add_i32 s30, s31, s21
	global_load_lds_dwordx4 v130, s[4:5]
	s_mov_b32 m0, s30
	s_nop 0
	global_load_lds_dwordx4 v134, s[28:29]
	s_add_i32 m0, s30, 0x2000
	s_nop 0
	global_load_lds_dwordx4 v130, s[28:29]
	s_add_u32 s4, s66, 0x80
	s_addc_u32 s5, s67, 0
	s_mov_b32 m0, s71
	s_nop 0
	global_load_lds_dwordx4 v136, s[4:5]
	s_mov_b32 m0, s72
	s_nop 0
	global_load_lds_dwordx4 v132, s[4:5]
	s_waitcnt vmcnt(6)
	s_waitcnt lgkmcnt(0)
	s_barrier
	s_setprio 1
	s_waitcnt lgkmcnt(0)
	v_mfma_f32_16x16x32_bf16 v[60:63], v[146:149], v[218:221], v[60:63]
	v_mfma_f32_16x16x32_bf16 v[52:55], v[154:157], v[218:221], v[52:55]
	v_mfma_f32_16x16x32_bf16 v[44:47], v[146:149], v[226:229], v[44:47]
	v_mfma_f32_16x16x32_bf16 v[36:39], v[154:157], v[226:229], v[36:39]
	v_mfma_f32_16x16x32_bf16 v[28:31], v[146:149], v[234:237], v[28:31]
	v_mfma_f32_16x16x32_bf16 v[20:23], v[154:157], v[234:237], v[20:23]
	v_mfma_f32_16x16x32_bf16 v[12:15], v[146:149], v[242:245], v[12:15]
	v_mfma_f32_16x16x32_bf16 v[4:7], v[154:157], v[242:245], v[4:7]
	v_mfma_f32_16x16x32_bf16 v[60:63], v[150:153], v[222:225], v[60:63]
	v_mfma_f32_16x16x32_bf16 v[52:55], v[158:161], v[222:225], v[52:55]
	v_mfma_f32_16x16x32_bf16 v[44:47], v[150:153], v[230:233], v[44:47]
	v_mfma_f32_16x16x32_bf16 v[36:39], v[158:161], v[230:233], v[36:39]
	v_mfma_f32_16x16x32_bf16 v[28:31], v[150:153], v[238:241], v[28:31]
	v_mfma_f32_16x16x32_bf16 v[20:23], v[158:161], v[238:241], v[20:23]
	v_mfma_f32_16x16x32_bf16 v[12:15], v[150:153], v[246:249], v[12:15]
	v_mfma_f32_16x16x32_bf16 v[4:7], v[158:161], v[246:249], v[4:7]
	s_setprio 0
	s_setprio 1
	v_mfma_f32_16x16x32_bf16 v[56:59], v[162:165], v[218:221], v[56:59]
	v_mfma_f32_16x16x32_bf16 v[48:51], v[170:173], v[218:221], v[48:51]
	v_mfma_f32_16x16x32_bf16 v[40:43], v[162:165], v[226:229], v[40:43]
	v_mfma_f32_16x16x32_bf16 v[32:35], v[170:173], v[226:229], v[32:35]
	v_mfma_f32_16x16x32_bf16 v[24:27], v[162:165], v[234:237], v[24:27]
	v_mfma_f32_16x16x32_bf16 v[16:19], v[170:173], v[234:237], v[16:19]
	v_mfma_f32_16x16x32_bf16 v[8:11], v[162:165], v[242:245], v[8:11]
	v_mfma_f32_16x16x32_bf16 v[0:3], v[170:173], v[242:245], v[0:3]
	v_mfma_f32_16x16x32_bf16 v[56:59], v[166:169], v[222:225], v[56:59]
	v_mfma_f32_16x16x32_bf16 v[48:51], v[174:177], v[222:225], v[48:51]
	v_mfma_f32_16x16x32_bf16 v[40:43], v[166:169], v[230:233], v[40:43]
	v_mfma_f32_16x16x32_bf16 v[32:35], v[174:177], v[230:233], v[32:35]
	v_mfma_f32_16x16x32_bf16 v[24:27], v[166:169], v[238:241], v[24:27]
	v_mfma_f32_16x16x32_bf16 v[16:19], v[174:177], v[238:241], v[16:19]
	v_mfma_f32_16x16x32_bf16 v[8:11], v[166:169], v[246:249], v[8:11]
	v_mfma_f32_16x16x32_bf16 v[0:3], v[174:177], v[246:249], v[0:3]
	s_setprio 0
	s_barrier
	s_add_i32 s52, s52, 2
	s_add_u32 s62, s62, 0x100
	s_addc_u32 s63, s63, 0
	s_add_u32 s49, s49, 0x100
	s_addc_u32 s51, s51, 0
	s_cmp_gt_u32 s52, 29
	s_cbranch_scc0 .LBB0_1319
	v_mov_b32_e32 v218, 0x2a00
	v_mov_b32_e32 v219, 0xf149f2ca
	v_mov_b32_e32 v220, 0xe00
	s_mov_b64 s[4:5], 0x80
	s_and_b64 vcc, exec, s[46:47]
	s_cbranch_vccz .LBB0_1322
	s_barrier
